# accumulator zeroing in GEMM unit headers with 64 v_mov_b64 instead of 128 v_mov_b32
# speedup vs baseline: 1.0051x; 1.0051x over previous
; template <class Epi, class Sched, bool ALIGN_EPI = false, bool SP2 = false>
; __device__ __forceinline__ void gemm_phase(PG8_LAS unsigned char* lds, const Gemm g, const Sched& S, const Epi& E) {
;     ...
; #pragma unroll
;         for (int a = 0; a < 2; ++a)
; #pragma unroll
;             for (int b = 0; b < 2; ++b)
; #pragma unroll
;                 for (int m = 0; m < 4; ++m)
; #pragma unroll
;                     for (int n = 0; n < 2; ++n) acc[a][b][m][n] = (f32x4){0.f, 0.f, 0.f, 0.f};
.LBB0_714:
	v_mov_b64_e32 v[0:1], 0
	v_mov_b64_e32 v[2:3], 0
	v_mov_b64_e32 v[4:5], 0
	v_mov_b64_e32 v[6:7], 0
	v_mov_b64_e32 v[8:9], 0
	v_mov_b64_e32 v[10:11], 0
	v_mov_b64_e32 v[12:13], 0
	v_mov_b64_e32 v[14:15], 0
	v_mov_b64_e32 v[16:17], 0
	v_mov_b64_e32 v[18:19], 0
	v_mov_b64_e32 v[20:21], 0
	v_mov_b64_e32 v[22:23], 0
	v_mov_b64_e32 v[24:25], 0
	v_mov_b64_e32 v[26:27], 0
	v_mov_b64_e32 v[28:29], 0
	v_mov_b64_e32 v[30:31], 0
	v_mov_b64_e32 v[32:33], 0
	v_mov_b64_e32 v[34:35], 0
	v_mov_b64_e32 v[36:37], 0
	v_mov_b64_e32 v[38:39], 0
	v_mov_b64_e32 v[40:41], 0
	v_mov_b64_e32 v[42:43], 0
	v_mov_b64_e32 v[44:45], 0
	v_mov_b64_e32 v[46:47], 0
	v_mov_b64_e32 v[48:49], 0
	v_mov_b64_e32 v[50:51], 0
	v_mov_b64_e32 v[52:53], 0
	v_mov_b64_e32 v[54:55], 0
	v_mov_b64_e32 v[56:57], 0
	v_mov_b64_e32 v[58:59], 0
	v_mov_b64_e32 v[60:61], 0
	v_mov_b64_e32 v[62:63], 0
	v_mov_b64_e32 v[64:65], 0
	v_mov_b64_e32 v[66:67], 0
	v_mov_b64_e32 v[68:69], 0
	v_mov_b64_e32 v[70:71], 0
	v_mov_b64_e32 v[72:73], 0
	v_mov_b64_e32 v[74:75], 0
	v_mov_b64_e32 v[76:77], 0
	v_mov_b64_e32 v[78:79], 0
	v_mov_b64_e32 v[80:81], 0
	v_mov_b64_e32 v[82:83], 0
	v_mov_b64_e32 v[84:85], 0
	v_mov_b64_e32 v[86:87], 0
	v_mov_b64_e32 v[88:89], 0
	v_mov_b64_e32 v[90:91], 0
	v_mov_b64_e32 v[92:93], 0
	v_mov_b64_e32 v[94:95], 0
	v_mov_b64_e32 v[96:97], 0
	v_mov_b64_e32 v[98:99], 0
	v_mov_b64_e32 v[100:101], 0
	v_mov_b64_e32 v[102:103], 0
	v_mov_b64_e32 v[104:105], 0
	v_mov_b64_e32 v[106:107], 0
	v_mov_b64_e32 v[108:109], 0
	v_mov_b64_e32 v[110:111], 0
	v_mov_b64_e32 v[112:113], 0
	v_mov_b64_e32 v[114:115], 0
	v_mov_b64_e32 v[116:117], 0
	v_mov_b64_e32 v[118:119], 0
	v_mov_b64_e32 v[120:121], 0
	v_mov_b64_e32 v[122:123], 0
	v_mov_b64_e32 v[124:125], 0
	v_mov_b64_e32 v[126:127], 0
	s_andn2_b64 vcc, exec, s[72:73]
	s_waitcnt vmcnt(0)
	s_waitcnt lgkmcnt(0)
	s_cbranch_vccnz .LBB0_717
	s_add_u32 s0, s46, 0x80
	s_addc_u32 s1, s47, 0
	s_add_u32 s20, s44, 0x100
	s_addc_u32 s21, s45, 0
	s_mov_b32 s28, 0

; template <class Epi, class Sched, bool ALIGN_EPI = false, bool SP2 = false>
; __device__ __forceinline__ void gemm_phase(PG8_LAS unsigned char* lds, const Gemm g, const Sched& S, const Epi& E) {
;     ...
; #pragma unroll
;         for (int a = 0; a < 2; ++a)
; #pragma unroll
;             for (int b = 0; b < 2; ++b)
; #pragma unroll
;                 for (int m = 0; m < 4; ++m)
; #pragma unroll
;                     for (int n = 0; n < 2; ++n) acc[a][b][m][n] = (f32x4){0.f, 0.f, 0.f, 0.f};
.LBB0_1047:
	v_mov_b64_e32 v[0:1], 0
	v_mov_b64_e32 v[2:3], 0
	v_mov_b64_e32 v[4:5], 0
	v_mov_b64_e32 v[6:7], 0
	v_mov_b64_e32 v[8:9], 0
	v_mov_b64_e32 v[10:11], 0
	v_mov_b64_e32 v[12:13], 0
	v_mov_b64_e32 v[14:15], 0
	v_mov_b64_e32 v[16:17], 0
	v_mov_b64_e32 v[18:19], 0
	v_mov_b64_e32 v[20:21], 0
	v_mov_b64_e32 v[22:23], 0
	v_mov_b64_e32 v[24:25], 0
	v_mov_b64_e32 v[26:27], 0
	v_mov_b64_e32 v[28:29], 0
	v_mov_b64_e32 v[30:31], 0
	v_mov_b64_e32 v[32:33], 0
	v_mov_b64_e32 v[34:35], 0
	v_mov_b64_e32 v[36:37], 0
	v_mov_b64_e32 v[38:39], 0
	v_mov_b64_e32 v[40:41], 0
	v_mov_b64_e32 v[42:43], 0
	v_mov_b64_e32 v[44:45], 0
	v_mov_b64_e32 v[46:47], 0
	v_mov_b64_e32 v[48:49], 0
	v_mov_b64_e32 v[50:51], 0
	v_mov_b64_e32 v[52:53], 0
	v_mov_b64_e32 v[54:55], 0
	v_mov_b64_e32 v[56:57], 0
	v_mov_b64_e32 v[58:59], 0
	v_mov_b64_e32 v[60:61], 0
	v_mov_b64_e32 v[62:63], 0
	v_mov_b64_e32 v[64:65], 0
	v_mov_b64_e32 v[66:67], 0
	v_mov_b64_e32 v[68:69], 0
	v_mov_b64_e32 v[70:71], 0
	v_mov_b64_e32 v[72:73], 0
	v_mov_b64_e32 v[74:75], 0
	v_mov_b64_e32 v[76:77], 0
	v_mov_b64_e32 v[78:79], 0
	v_mov_b64_e32 v[80:81], 0
	v_mov_b64_e32 v[82:83], 0
	v_mov_b64_e32 v[84:85], 0
	v_mov_b64_e32 v[86:87], 0
	v_mov_b64_e32 v[88:89], 0
	v_mov_b64_e32 v[90:91], 0
	v_mov_b64_e32 v[92:93], 0
	v_mov_b64_e32 v[94:95], 0
	v_mov_b64_e32 v[96:97], 0
	v_mov_b64_e32 v[98:99], 0
	v_mov_b64_e32 v[100:101], 0
	v_mov_b64_e32 v[102:103], 0
	v_mov_b64_e32 v[104:105], 0
	v_mov_b64_e32 v[106:107], 0
	v_mov_b64_e32 v[108:109], 0
	v_mov_b64_e32 v[110:111], 0
	v_mov_b64_e32 v[112:113], 0
	v_mov_b64_e32 v[114:115], 0
	v_mov_b64_e32 v[116:117], 0
	v_mov_b64_e32 v[118:119], 0
	v_mov_b64_e32 v[120:121], 0
	v_mov_b64_e32 v[122:123], 0
	v_mov_b64_e32 v[124:125], 0
	v_mov_b64_e32 v[126:127], 0
	s_andn2_b64 vcc, exec, s[72:73]
	s_waitcnt vmcnt(0)
	s_cbranch_vccnz .LBB0_1050
	s_add_u32 s42, s42, 0x80
	s_addc_u32 s43, s43, 0
	s_add_u32 s57, s44, 0x100
	s_addc_u32 s58, s45, 0
	s_mov_b32 s44, 0

; template <class Epi, class Sched, bool ALIGN_EPI = false, bool SP2 = false>
; __device__ __forceinline__ void gemm_phase(PG8_LAS unsigned char* lds, const Gemm g, const Sched& S, const Epi& E) {
;     ...
; #pragma unroll
;         for (int a = 0; a < 2; ++a)
; #pragma unroll
;             for (int b = 0; b < 2; ++b)
; #pragma unroll
;                 for (int m = 0; m < 4; ++m)
; #pragma unroll
;                     for (int n = 0; n < 2; ++n) acc[a][b][m][n] = (f32x4){0.f, 0.f, 0.f, 0.f};
.LBB0_1166:
	v_mov_b64_e32 v[0:1], 0
	v_mov_b64_e32 v[2:3], 0
	v_mov_b64_e32 v[4:5], 0
	v_mov_b64_e32 v[6:7], 0
	v_mov_b64_e32 v[8:9], 0
	v_mov_b64_e32 v[10:11], 0
	v_mov_b64_e32 v[12:13], 0
	v_mov_b64_e32 v[14:15], 0
	v_mov_b64_e32 v[16:17], 0
	v_mov_b64_e32 v[18:19], 0
	v_mov_b64_e32 v[20:21], 0
	v_mov_b64_e32 v[22:23], 0
	v_mov_b64_e32 v[24:25], 0
	v_mov_b64_e32 v[26:27], 0
	v_mov_b64_e32 v[28:29], 0
	v_mov_b64_e32 v[30:31], 0
	v_mov_b64_e32 v[32:33], 0
	v_mov_b64_e32 v[34:35], 0
	v_mov_b64_e32 v[36:37], 0
	v_mov_b64_e32 v[38:39], 0
	v_mov_b64_e32 v[40:41], 0
	v_mov_b64_e32 v[42:43], 0
	v_mov_b64_e32 v[44:45], 0
	v_mov_b64_e32 v[46:47], 0
	v_mov_b64_e32 v[48:49], 0
	v_mov_b64_e32 v[50:51], 0
	v_mov_b64_e32 v[52:53], 0
	v_mov_b64_e32 v[54:55], 0
	v_mov_b64_e32 v[56:57], 0
	v_mov_b64_e32 v[58:59], 0
	v_mov_b64_e32 v[60:61], 0
	v_mov_b64_e32 v[62:63], 0
	v_mov_b64_e32 v[64:65], 0
	v_mov_b64_e32 v[66:67], 0
	v_mov_b64_e32 v[68:69], 0
	v_mov_b64_e32 v[70:71], 0
	v_mov_b64_e32 v[72:73], 0
	v_mov_b64_e32 v[74:75], 0
	v_mov_b64_e32 v[76:77], 0
	v_mov_b64_e32 v[78:79], 0
	v_mov_b64_e32 v[80:81], 0
	v_mov_b64_e32 v[82:83], 0
	v_mov_b64_e32 v[84:85], 0
	v_mov_b64_e32 v[86:87], 0
	v_mov_b64_e32 v[88:89], 0
	v_mov_b64_e32 v[90:91], 0
	v_mov_b64_e32 v[92:93], 0
	v_mov_b64_e32 v[94:95], 0
	v_mov_b64_e32 v[96:97], 0
	v_mov_b64_e32 v[98:99], 0
	v_mov_b64_e32 v[100:101], 0
	v_mov_b64_e32 v[102:103], 0
	v_mov_b64_e32 v[104:105], 0
	v_mov_b64_e32 v[106:107], 0
	v_mov_b64_e32 v[108:109], 0
	v_mov_b64_e32 v[110:111], 0
	v_mov_b64_e32 v[112:113], 0
	v_mov_b64_e32 v[114:115], 0
	v_mov_b64_e32 v[116:117], 0
	v_mov_b64_e32 v[118:119], 0
	v_mov_b64_e32 v[120:121], 0
	v_mov_b64_e32 v[122:123], 0
	v_mov_b64_e32 v[124:125], 0
	v_mov_b64_e32 v[126:127], 0
	s_andn2_b64 vcc, exec, s[72:73]
	s_waitcnt vmcnt(0)
	s_cbranch_vccnz .LBB0_1169
	s_add_u32 s4, s4, 0x80
	s_addc_u32 s5, s5, 0
	s_add_u32 s20, s22, 0x100
	s_addc_u32 s21, s23, 0
	s_mov_b32 s22, 0
